# batched loads in the FFN-out residual epilogue (6 load batches per tile instead of 48 serial round trips)
# speedup vs baseline: 1.0296x; 1.0008x over previous
.LBB0_46:
	s_lshl_b32 s20, s61, 7
	v_add_u32_e32 v110, s20, v114
	v_lshlrev_b32_e32 v110, 2, v110
	v_mov_b32_e32 v111, 0
	v_lshl_add_u64 v[104:105], s[14:15], 0, v[110:111]
	s_mul_i32 s20, s60, 0xc0
	v_add3_u32 v108, s20, v113, v112
	v_subrev_co_u32_e32 v109, vcc, 0x1000, v108
	v_lshrrev_b32_e32 v109, 11, v109
	v_add_u32_e32 v109, 1, v109
	s_nop 0
	v_cndmask_b32_e64 v109, v109, 0, vcc
	v_add_u32_e32 v124, s48, v109
	v_mul_u32_u24_e32 v124, 0x6000, v124
	v_add_u32_e32 v124, v124, v110
	v_mov_b32_e32 v125, 0
	v_lshl_add_u64 v[98:99], s[50:51], 0, v[124:125]
	v_add_u32_e32 v124, s52, v109
	v_mul_u32_u24_e32 v124, 0x6000, v124
	v_add_u32_e32 v124, v124, v110
	v_lshl_add_u64 v[106:107], s[46:47], 0, v[124:125]
	v_lshlrev_b32_e32 v124, 12, v108
	v_add_u32_e32 v124, v124, v110
	v_lshl_add_u64 v[100:101], s[6:7], 0, v[124:125]
	v_lshrrev_b32_e32 v124, 1, v124
	v_lshl_add_u64 v[102:103], s[8:9], 0, v[124:125]
	v_mov_b32_e32 v122, 0
	v_mov_b32_e32 v123, 0
	global_load_dwordx4 v[180:183], v[98:99], off offset:0
	global_load_dwordx4 v[196:199], v[100:101], off offset:0
	global_load_dwordx4 v[184:187], v[98:99], off offset:32
	global_load_dwordx4 v[200:203], v[100:101], off offset:32
	global_load_dwordx4 v[188:191], v[98:99], off offset:64
	global_load_dwordx4 v[204:207], v[100:101], off offset:64
	global_load_dwordx4 v[192:195], v[98:99], off offset:96
	global_load_dwordx4 v[208:211], v[100:101], off offset:96
	s_and_b64 vcc, exec, s[54:55]
	s_cbranch_vccz .Lrs_a_nl_0_0
	global_load_dwordx4 v[212:215], v[104:105], off offset:0
	global_load_dwordx4 v[138:141], v[106:107], off offset:0
	global_load_dwordx4 v[216:219], v[104:105], off offset:32
	global_load_dwordx4 v[142:145], v[106:107], off offset:32
	global_load_dwordx4 v[220:223], v[104:105], off offset:64
	global_load_dwordx4 v[146:149], v[106:107], off offset:64
	global_load_dwordx4 v[134:137], v[104:105], off offset:96
	global_load_dwordx4 v[118:121], v[106:107], off offset:96
.Lrs_a_nl_0_0:
	s_waitcnt vmcnt(0)
	v_pk_fma_f32 v[196:197], v[82:83], v[180:181], v[196:197]
	v_pk_fma_f32 v[198:199], v[84:85], v[182:183], v[198:199]
	v_pk_fma_f32 v[200:201], v[86:87], v[184:185], v[200:201]
	v_pk_fma_f32 v[202:203], v[88:89], v[186:187], v[202:203]
	v_pk_fma_f32 v[204:205], v[90:91], v[188:189], v[204:205]
	v_pk_fma_f32 v[206:207], v[92:93], v[190:191], v[206:207]
	v_pk_fma_f32 v[208:209], v[94:95], v[192:193], v[208:209]
	v_pk_fma_f32 v[210:211], v[96:97], v[194:195], v[210:211]
	global_store_dwordx4 v[100:101], v[196:199], off offset:0
	global_store_dwordx4 v[100:101], v[200:203], off offset:32
	global_store_dwordx4 v[100:101], v[204:207], off offset:64
	global_store_dwordx4 v[100:101], v[208:211], off offset:96
	s_cbranch_vccz .Lrs_a_nx_0_0
	v_pk_fma_f32 v[122:123], v[196:197], v[196:197], v[122:123]
	v_pk_fma_f32 v[122:123], v[198:199], v[198:199], v[122:123]
	v_pk_add_f32 v[138:139], v[138:139], 1.0 op_sel_hi:[1,0]
	v_pk_add_f32 v[140:141], v[140:141], 1.0 op_sel_hi:[1,0]
	v_pk_mul_f32 v[212:213], v[196:197], v[212:213]
	v_pk_mul_f32 v[214:215], v[198:199], v[214:215]
	v_pk_mul_f32 v[212:213], v[212:213], v[138:139]
	v_pk_mul_f32 v[214:215], v[214:215], v[140:141]
	v_cvt_pk_f16_f32 v212, v212, v213
	v_cvt_pk_f16_f32 v213, v214, v215
	v_pk_fma_f32 v[122:123], v[200:201], v[200:201], v[122:123]
	v_pk_fma_f32 v[122:123], v[202:203], v[202:203], v[122:123]
	v_pk_add_f32 v[142:143], v[142:143], 1.0 op_sel_hi:[1,0]
	v_pk_add_f32 v[144:145], v[144:145], 1.0 op_sel_hi:[1,0]
	v_pk_mul_f32 v[216:217], v[200:201], v[216:217]
	v_pk_mul_f32 v[218:219], v[202:203], v[218:219]
	v_pk_mul_f32 v[216:217], v[216:217], v[142:143]
	v_pk_mul_f32 v[218:219], v[218:219], v[144:145]
	v_cvt_pk_f16_f32 v216, v216, v217
	v_cvt_pk_f16_f32 v217, v218, v219
	v_pk_fma_f32 v[122:123], v[204:205], v[204:205], v[122:123]
	v_pk_fma_f32 v[122:123], v[206:207], v[206:207], v[122:123]
	v_pk_add_f32 v[146:147], v[146:147], 1.0 op_sel_hi:[1,0]
	v_pk_add_f32 v[148:149], v[148:149], 1.0 op_sel_hi:[1,0]
	v_pk_mul_f32 v[220:221], v[204:205], v[220:221]
	v_pk_mul_f32 v[222:223], v[206:207], v[222:223]
	v_pk_mul_f32 v[220:221], v[220:221], v[146:147]
	v_pk_mul_f32 v[222:223], v[222:223], v[148:149]
	v_cvt_pk_f16_f32 v220, v220, v221
	v_cvt_pk_f16_f32 v221, v222, v223
	v_pk_fma_f32 v[122:123], v[208:209], v[208:209], v[122:123]
	v_pk_fma_f32 v[122:123], v[210:211], v[210:211], v[122:123]
	v_pk_add_f32 v[118:119], v[118:119], 1.0 op_sel_hi:[1,0]
	v_pk_add_f32 v[120:121], v[120:121], 1.0 op_sel_hi:[1,0]
	v_pk_mul_f32 v[134:135], v[208:209], v[134:135]
	v_pk_mul_f32 v[136:137], v[210:211], v[136:137]
	v_pk_mul_f32 v[134:135], v[134:135], v[118:119]
	v_pk_mul_f32 v[136:137], v[136:137], v[120:121]
	v_cvt_pk_f16_f32 v134, v134, v135
	v_cvt_pk_f16_f32 v135, v136, v137
	s_nop 0
	global_store_dwordx2 v[102:103], v[212:213], off offset:0
	global_store_dwordx2 v[102:103], v[216:217], off offset:16
	global_store_dwordx2 v[102:103], v[220:221], off offset:32
	global_store_dwordx2 v[102:103], v[134:135], off offset:48
.Lrs_a_nx_0_0:
	global_load_dwordx4 v[180:183], v[98:99], off offset:128
	global_load_dwordx4 v[196:199], v[100:101], off offset:128
	global_load_dwordx4 v[184:187], v[98:99], off offset:160
	global_load_dwordx4 v[200:203], v[100:101], off offset:160
	global_load_dwordx4 v[188:191], v[98:99], off offset:192
	global_load_dwordx4 v[204:207], v[100:101], off offset:192
	global_load_dwordx4 v[192:195], v[98:99], off offset:224
	global_load_dwordx4 v[208:211], v[100:101], off offset:224
	s_and_b64 vcc, exec, s[54:55]
	s_cbranch_vccz .Lrs_a_nl_0_1
	global_load_dwordx4 v[212:215], v[104:105], off offset:128
	global_load_dwordx4 v[138:141], v[106:107], off offset:128
	global_load_dwordx4 v[216:219], v[104:105], off offset:160
	global_load_dwordx4 v[142:145], v[106:107], off offset:160
	global_load_dwordx4 v[220:223], v[104:105], off offset:192
	global_load_dwordx4 v[146:149], v[106:107], off offset:192
	global_load_dwordx4 v[134:137], v[104:105], off offset:224
	global_load_dwordx4 v[118:121], v[106:107], off offset:224
.Lrs_a_nl_0_1:
	s_waitcnt vmcnt(0)
	v_pk_fma_f32 v[196:197], v[66:67], v[180:181], v[196:197]
	v_pk_fma_f32 v[198:199], v[68:69], v[182:183], v[198:199]
	v_pk_fma_f32 v[200:201], v[70:71], v[184:185], v[200:201]
	v_pk_fma_f32 v[202:203], v[72:73], v[186:187], v[202:203]
	v_pk_fma_f32 v[204:205], v[74:75], v[188:189], v[204:205]
	v_pk_fma_f32 v[206:207], v[76:77], v[190:191], v[206:207]
	v_pk_fma_f32 v[208:209], v[78:79], v[192:193], v[208:209]
	v_pk_fma_f32 v[210:211], v[80:81], v[194:195], v[210:211]
	global_store_dwordx4 v[100:101], v[196:199], off offset:128
	global_store_dwordx4 v[100:101], v[200:203], off offset:160
	global_store_dwordx4 v[100:101], v[204:207], off offset:192
	global_store_dwordx4 v[100:101], v[208:211], off offset:224
	s_cbranch_vccz .Lrs_a_nx_0_1
	v_pk_fma_f32 v[122:123], v[196:197], v[196:197], v[122:123]
	v_pk_fma_f32 v[122:123], v[198:199], v[198:199], v[122:123]
	v_pk_add_f32 v[138:139], v[138:139], 1.0 op_sel_hi:[1,0]
	v_pk_add_f32 v[140:141], v[140:141], 1.0 op_sel_hi:[1,0]
	v_pk_mul_f32 v[212:213], v[196:197], v[212:213]
	v_pk_mul_f32 v[214:215], v[198:199], v[214:215]
	v_pk_mul_f32 v[212:213], v[212:213], v[138:139]
	v_pk_mul_f32 v[214:215], v[214:215], v[140:141]
	v_cvt_pk_f16_f32 v212, v212, v213
	v_cvt_pk_f16_f32 v213, v214, v215
	v_pk_fma_f32 v[122:123], v[200:201], v[200:201], v[122:123]
	v_pk_fma_f32 v[122:123], v[202:203], v[202:203], v[122:123]
	v_pk_add_f32 v[142:143], v[142:143], 1.0 op_sel_hi:[1,0]
	v_pk_add_f32 v[144:145], v[144:145], 1.0 op_sel_hi:[1,0]
	v_pk_mul_f32 v[216:217], v[200:201], v[216:217]
	v_pk_mul_f32 v[218:219], v[202:203], v[218:219]
	v_pk_mul_f32 v[216:217], v[216:217], v[142:143]
	v_pk_mul_f32 v[218:219], v[218:219], v[144:145]
	v_cvt_pk_f16_f32 v216, v216, v217
	v_cvt_pk_f16_f32 v217, v218, v219
	v_pk_fma_f32 v[122:123], v[204:205], v[204:205], v[122:123]
	v_pk_fma_f32 v[122:123], v[206:207], v[206:207], v[122:123]
	v_pk_add_f32 v[146:147], v[146:147], 1.0 op_sel_hi:[1,0]
	v_pk_add_f32 v[148:149], v[148:149], 1.0 op_sel_hi:[1,0]
	v_pk_mul_f32 v[220:221], v[204:205], v[220:221]
	v_pk_mul_f32 v[222:223], v[206:207], v[222:223]
	v_pk_mul_f32 v[220:221], v[220:221], v[146:147]
	v_pk_mul_f32 v[222:223], v[222:223], v[148:149]
	v_cvt_pk_f16_f32 v220, v220, v221
	v_cvt_pk_f16_f32 v221, v222, v223
	v_pk_fma_f32 v[122:123], v[208:209], v[208:209], v[122:123]
	v_pk_fma_f32 v[122:123], v[210:211], v[210:211], v[122:123]
	v_pk_add_f32 v[118:119], v[118:119], 1.0 op_sel_hi:[1,0]
	v_pk_add_f32 v[120:121], v[120:121], 1.0 op_sel_hi:[1,0]
	v_pk_mul_f32 v[134:135], v[208:209], v[134:135]
	v_pk_mul_f32 v[136:137], v[210:211], v[136:137]
	v_pk_mul_f32 v[134:135], v[134:135], v[118:119]
	v_pk_mul_f32 v[136:137], v[136:137], v[120:121]
	v_cvt_pk_f16_f32 v134, v134, v135
	v_cvt_pk_f16_f32 v135, v136, v137
	s_nop 0
	global_store_dwordx2 v[102:103], v[212:213], off offset:64
	global_store_dwordx2 v[102:103], v[216:217], off offset:80
	global_store_dwordx2 v[102:103], v[220:221], off offset:96
	global_store_dwordx2 v[102:103], v[134:135], off offset:112
.Lrs_a_nx_0_1:
	s_and_b64 vcc, exec, s[54:55]
	s_cbranch_vccz .Lrs_a_ns_0
	v_add_f32_e32 v122, v122, v123
	v_mov_b32_e32 v123, v122
	s_nop 1
	v_permlane32_swap_b32_e32 v123, v122
	v_add_f32_e32 v122, v122, v123
	v_lshlrev_b32_e32 v124, 2, v108
	v_lshl_add_u64 v[124:125], s[12:13], 0, v[124:125]
	s_mov_b64 s[42:43], exec
	s_and_b64 exec, exec, s[40:41]
	global_atomic_add_f32 v[124:125], v122, off
	s_mov_b64 exec, s[42:43]
.Lrs_a_ns_0:
	v_add_u32_e32 v108, 32, v108
	v_subrev_co_u32_e32 v109, vcc, 0x1000, v108
	v_lshrrev_b32_e32 v109, 11, v109
	v_add_u32_e32 v109, 1, v109
	s_nop 0
	v_cndmask_b32_e64 v109, v109, 0, vcc
	v_add_u32_e32 v124, s48, v109
	v_mul_u32_u24_e32 v124, 0x6000, v124
	v_add_u32_e32 v124, v124, v110
	v_mov_b32_e32 v125, 0
	v_lshl_add_u64 v[98:99], s[50:51], 0, v[124:125]
	v_add_u32_e32 v124, s52, v109
	v_mul_u32_u24_e32 v124, 0x6000, v124
	v_add_u32_e32 v124, v124, v110
	v_lshl_add_u64 v[106:107], s[46:47], 0, v[124:125]
	v_lshlrev_b32_e32 v124, 12, v108
	v_add_u32_e32 v124, v124, v110
	v_lshl_add_u64 v[100:101], s[6:7], 0, v[124:125]
	v_lshrrev_b32_e32 v124, 1, v124
	v_lshl_add_u64 v[102:103], s[8:9], 0, v[124:125]
	v_mov_b32_e32 v122, 0
	v_mov_b32_e32 v123, 0
	global_load_dwordx4 v[180:183], v[98:99], off offset:0
	global_load_dwordx4 v[196:199], v[100:101], off offset:0
	global_load_dwordx4 v[184:187], v[98:99], off offset:32
	global_load_dwordx4 v[200:203], v[100:101], off offset:32
	global_load_dwordx4 v[188:191], v[98:99], off offset:64
	global_load_dwordx4 v[204:207], v[100:101], off offset:64
	global_load_dwordx4 v[192:195], v[98:99], off offset:96
	global_load_dwordx4 v[208:211], v[100:101], off offset:96
	s_and_b64 vcc, exec, s[54:55]
	s_cbranch_vccz .Lrs_a_nl_1_0
	global_load_dwordx4 v[212:215], v[104:105], off offset:0
	global_load_dwordx4 v[138:141], v[106:107], off offset:0
	global_load_dwordx4 v[216:219], v[104:105], off offset:32
	global_load_dwordx4 v[142:145], v[106:107], off offset:32
	global_load_dwordx4 v[220:223], v[104:105], off offset:64
	global_load_dwordx4 v[146:149], v[106:107], off offset:64
	global_load_dwordx4 v[134:137], v[104:105], off offset:96
	global_load_dwordx4 v[118:121], v[106:107], off offset:96
.Lrs_a_nl_1_0:
	s_waitcnt vmcnt(0)
	v_pk_fma_f32 v[196:197], v[50:51], v[180:181], v[196:197]
	v_pk_fma_f32 v[198:199], v[52:53], v[182:183], v[198:199]
	v_pk_fma_f32 v[200:201], v[54:55], v[184:185], v[200:201]
	v_pk_fma_f32 v[202:203], v[56:57], v[186:187], v[202:203]
	v_pk_fma_f32 v[204:205], v[58:59], v[188:189], v[204:205]
	v_pk_fma_f32 v[206:207], v[60:61], v[190:191], v[206:207]
	v_pk_fma_f32 v[208:209], v[62:63], v[192:193], v[208:209]
	v_pk_fma_f32 v[210:211], v[64:65], v[194:195], v[210:211]
	global_store_dwordx4 v[100:101], v[196:199], off offset:0
	global_store_dwordx4 v[100:101], v[200:203], off offset:32
	global_store_dwordx4 v[100:101], v[204:207], off offset:64
	global_store_dwordx4 v[100:101], v[208:211], off offset:96
	s_cbranch_vccz .Lrs_a_nx_1_0
	v_pk_fma_f32 v[122:123], v[196:197], v[196:197], v[122:123]
	v_pk_fma_f32 v[122:123], v[198:199], v[198:199], v[122:123]
	v_pk_add_f32 v[138:139], v[138:139], 1.0 op_sel_hi:[1,0]
	v_pk_add_f32 v[140:141], v[140:141], 1.0 op_sel_hi:[1,0]
	v_pk_mul_f32 v[212:213], v[196:197], v[212:213]
	v_pk_mul_f32 v[214:215], v[198:199], v[214:215]
	v_pk_mul_f32 v[212:213], v[212:213], v[138:139]
	v_pk_mul_f32 v[214:215], v[214:215], v[140:141]
	v_cvt_pk_f16_f32 v212, v212, v213
	v_cvt_pk_f16_f32 v213, v214, v215
	v_pk_fma_f32 v[122:123], v[200:201], v[200:201], v[122:123]
	v_pk_fma_f32 v[122:123], v[202:203], v[202:203], v[122:123]
	v_pk_add_f32 v[142:143], v[142:143], 1.0 op_sel_hi:[1,0]
	v_pk_add_f32 v[144:145], v[144:145], 1.0 op_sel_hi:[1,0]
	v_pk_mul_f32 v[216:217], v[200:201], v[216:217]
	v_pk_mul_f32 v[218:219], v[202:203], v[218:219]
	v_pk_mul_f32 v[216:217], v[216:217], v[142:143]
	v_pk_mul_f32 v[218:219], v[218:219], v[144:145]
	v_cvt_pk_f16_f32 v216, v216, v217
	v_cvt_pk_f16_f32 v217, v218, v219
	v_pk_fma_f32 v[122:123], v[204:205], v[204:205], v[122:123]
	v_pk_fma_f32 v[122:123], v[206:207], v[206:207], v[122:123]
	v_pk_add_f32 v[146:147], v[146:147], 1.0 op_sel_hi:[1,0]
	v_pk_add_f32 v[148:149], v[148:149], 1.0 op_sel_hi:[1,0]
	v_pk_mul_f32 v[220:221], v[204:205], v[220:221]
	v_pk_mul_f32 v[222:223], v[206:207], v[222:223]
	v_pk_mul_f32 v[220:221], v[220:221], v[146:147]
	v_pk_mul_f32 v[222:223], v[222:223], v[148:149]
	v_cvt_pk_f16_f32 v220, v220, v221
	v_cvt_pk_f16_f32 v221, v222, v223
	v_pk_fma_f32 v[122:123], v[208:209], v[208:209], v[122:123]
	v_pk_fma_f32 v[122:123], v[210:211], v[210:211], v[122:123]
	v_pk_add_f32 v[118:119], v[118:119], 1.0 op_sel_hi:[1,0]
	v_pk_add_f32 v[120:121], v[120:121], 1.0 op_sel_hi:[1,0]
	v_pk_mul_f32 v[134:135], v[208:209], v[134:135]
	v_pk_mul_f32 v[136:137], v[210:211], v[136:137]
	v_pk_mul_f32 v[134:135], v[134:135], v[118:119]
	v_pk_mul_f32 v[136:137], v[136:137], v[120:121]
	v_cvt_pk_f16_f32 v134, v134, v135
	v_cvt_pk_f16_f32 v135, v136, v137
	s_nop 0
	global_store_dwordx2 v[102:103], v[212:213], off offset:0
	global_store_dwordx2 v[102:103], v[216:217], off offset:16
	global_store_dwordx2 v[102:103], v[220:221], off offset:32
	global_store_dwordx2 v[102:103], v[134:135], off offset:48

.Lrs_a_nl_1_1:
	s_waitcnt vmcnt(0)
	v_pk_fma_f32 v[196:197], v[34:35], v[180:181], v[196:197]
	v_pk_fma_f32 v[198:199], v[36:37], v[182:183], v[198:199]
	v_pk_fma_f32 v[200:201], v[38:39], v[184:185], v[200:201]
	v_pk_fma_f32 v[202:203], v[40:41], v[186:187], v[202:203]
	v_pk_fma_f32 v[204:205], v[42:43], v[188:189], v[204:205]
	v_pk_fma_f32 v[206:207], v[44:45], v[190:191], v[206:207]
	v_pk_fma_f32 v[208:209], v[46:47], v[192:193], v[208:209]
	v_pk_fma_f32 v[210:211], v[48:49], v[194:195], v[210:211]
	global_store_dwordx4 v[100:101], v[196:199], off offset:128
	global_store_dwordx4 v[100:101], v[200:203], off offset:160
	global_store_dwordx4 v[100:101], v[204:207], off offset:192
	global_store_dwordx4 v[100:101], v[208:211], off offset:224
	s_cbranch_vccz .Lrs_a_nx_1_1
	v_pk_fma_f32 v[122:123], v[196:197], v[196:197], v[122:123]
	v_pk_fma_f32 v[122:123], v[198:199], v[198:199], v[122:123]
	v_pk_add_f32 v[138:139], v[138:139], 1.0 op_sel_hi:[1,0]
	v_pk_add_f32 v[140:141], v[140:141], 1.0 op_sel_hi:[1,0]
	v_pk_mul_f32 v[212:213], v[196:197], v[212:213]
	v_pk_mul_f32 v[214:215], v[198:199], v[214:215]
	v_pk_mul_f32 v[212:213], v[212:213], v[138:139]
	v_pk_mul_f32 v[214:215], v[214:215], v[140:141]
	v_cvt_pk_f16_f32 v212, v212, v213
	v_cvt_pk_f16_f32 v213, v214, v215
	v_pk_fma_f32 v[122:123], v[200:201], v[200:201], v[122:123]
	v_pk_fma_f32 v[122:123], v[202:203], v[202:203], v[122:123]
	v_pk_add_f32 v[142:143], v[142:143], 1.0 op_sel_hi:[1,0]
	v_pk_add_f32 v[144:145], v[144:145], 1.0 op_sel_hi:[1,0]
	v_pk_mul_f32 v[216:217], v[200:201], v[216:217]
	v_pk_mul_f32 v[218:219], v[202:203], v[218:219]
	v_pk_mul_f32 v[216:217], v[216:217], v[142:143]
	v_pk_mul_f32 v[218:219], v[218:219], v[144:145]
	v_cvt_pk_f16_f32 v216, v216, v217
	v_cvt_pk_f16_f32 v217, v218, v219
	v_pk_fma_f32 v[122:123], v[204:205], v[204:205], v[122:123]
	v_pk_fma_f32 v[122:123], v[206:207], v[206:207], v[122:123]
	v_pk_add_f32 v[146:147], v[146:147], 1.0 op_sel_hi:[1,0]
	v_pk_add_f32 v[148:149], v[148:149], 1.0 op_sel_hi:[1,0]
	v_pk_mul_f32 v[220:221], v[204:205], v[220:221]
	v_pk_mul_f32 v[222:223], v[206:207], v[222:223]
	v_pk_mul_f32 v[220:221], v[220:221], v[146:147]
	v_pk_mul_f32 v[222:223], v[222:223], v[148:149]
	v_cvt_pk_f16_f32 v220, v220, v221
	v_cvt_pk_f16_f32 v221, v222, v223
	v_pk_fma_f32 v[122:123], v[208:209], v[208:209], v[122:123]
	v_pk_fma_f32 v[122:123], v[210:211], v[210:211], v[122:123]
	v_pk_add_f32 v[118:119], v[118:119], 1.0 op_sel_hi:[1,0]
	v_pk_add_f32 v[120:121], v[120:121], 1.0 op_sel_hi:[1,0]
	v_pk_mul_f32 v[134:135], v[208:209], v[134:135]
	v_pk_mul_f32 v[136:137], v[210:211], v[136:137]
	v_pk_mul_f32 v[134:135], v[134:135], v[118:119]
	v_pk_mul_f32 v[136:137], v[136:137], v[120:121]
	v_cvt_pk_f16_f32 v134, v134, v135
	v_cvt_pk_f16_f32 v135, v136, v137
	s_nop 0
	global_store_dwordx2 v[102:103], v[212:213], off offset:64
	global_store_dwordx2 v[102:103], v[216:217], off offset:80
	global_store_dwordx2 v[102:103], v[220:221], off offset:96
	global_store_dwordx2 v[102:103], v[134:135], off offset:112

.Lrs_a_nl_2_0:
	s_waitcnt vmcnt(0)
	v_pk_fma_f32 v[196:197], v[18:19], v[180:181], v[196:197]
	v_pk_fma_f32 v[198:199], v[20:21], v[182:183], v[198:199]
	v_pk_fma_f32 v[200:201], v[22:23], v[184:185], v[200:201]
	v_pk_fma_f32 v[202:203], v[24:25], v[186:187], v[202:203]
	v_pk_fma_f32 v[204:205], v[26:27], v[188:189], v[204:205]
	v_pk_fma_f32 v[206:207], v[28:29], v[190:191], v[206:207]
	v_pk_fma_f32 v[208:209], v[30:31], v[192:193], v[208:209]
	v_pk_fma_f32 v[210:211], v[32:33], v[194:195], v[210:211]
	global_store_dwordx4 v[100:101], v[196:199], off offset:0
	global_store_dwordx4 v[100:101], v[200:203], off offset:32
	global_store_dwordx4 v[100:101], v[204:207], off offset:64
	global_store_dwordx4 v[100:101], v[208:211], off offset:96
	s_cbranch_vccz .Lrs_a_nx_2_0
	v_pk_fma_f32 v[122:123], v[196:197], v[196:197], v[122:123]
	v_pk_fma_f32 v[122:123], v[198:199], v[198:199], v[122:123]
	v_pk_add_f32 v[138:139], v[138:139], 1.0 op_sel_hi:[1,0]
	v_pk_add_f32 v[140:141], v[140:141], 1.0 op_sel_hi:[1,0]
	v_pk_mul_f32 v[212:213], v[196:197], v[212:213]
	v_pk_mul_f32 v[214:215], v[198:199], v[214:215]
	v_pk_mul_f32 v[212:213], v[212:213], v[138:139]
	v_pk_mul_f32 v[214:215], v[214:215], v[140:141]
	v_cvt_pk_f16_f32 v212, v212, v213
	v_cvt_pk_f16_f32 v213, v214, v215
	v_pk_fma_f32 v[122:123], v[200:201], v[200:201], v[122:123]
	v_pk_fma_f32 v[122:123], v[202:203], v[202:203], v[122:123]
	v_pk_add_f32 v[142:143], v[142:143], 1.0 op_sel_hi:[1,0]
	v_pk_add_f32 v[144:145], v[144:145], 1.0 op_sel_hi:[1,0]
	v_pk_mul_f32 v[216:217], v[200:201], v[216:217]
	v_pk_mul_f32 v[218:219], v[202:203], v[218:219]
	v_pk_mul_f32 v[216:217], v[216:217], v[142:143]
	v_pk_mul_f32 v[218:219], v[218:219], v[144:145]
	v_cvt_pk_f16_f32 v216, v216, v217
	v_cvt_pk_f16_f32 v217, v218, v219
	v_pk_fma_f32 v[122:123], v[204:205], v[204:205], v[122:123]
	v_pk_fma_f32 v[122:123], v[206:207], v[206:207], v[122:123]
	v_pk_add_f32 v[146:147], v[146:147], 1.0 op_sel_hi:[1,0]
	v_pk_add_f32 v[148:149], v[148:149], 1.0 op_sel_hi:[1,0]
	v_pk_mul_f32 v[220:221], v[204:205], v[220:221]
	v_pk_mul_f32 v[222:223], v[206:207], v[222:223]
	v_pk_mul_f32 v[220:221], v[220:221], v[146:147]
	v_pk_mul_f32 v[222:223], v[222:223], v[148:149]
	v_cvt_pk_f16_f32 v220, v220, v221
	v_cvt_pk_f16_f32 v221, v222, v223
	v_pk_fma_f32 v[122:123], v[208:209], v[208:209], v[122:123]
	v_pk_fma_f32 v[122:123], v[210:211], v[210:211], v[122:123]
	v_pk_add_f32 v[118:119], v[118:119], 1.0 op_sel_hi:[1,0]
	v_pk_add_f32 v[120:121], v[120:121], 1.0 op_sel_hi:[1,0]
	v_pk_mul_f32 v[134:135], v[208:209], v[134:135]
	v_pk_mul_f32 v[136:137], v[210:211], v[136:137]
	v_pk_mul_f32 v[134:135], v[134:135], v[118:119]
	v_pk_mul_f32 v[136:137], v[136:137], v[120:121]
	v_cvt_pk_f16_f32 v134, v134, v135
	v_cvt_pk_f16_f32 v135, v136, v137
	s_nop 0
	global_store_dwordx2 v[102:103], v[212:213], off offset:0
	global_store_dwordx2 v[102:103], v[216:217], off offset:16
	global_store_dwordx2 v[102:103], v[220:221], off offset:32
	global_store_dwordx2 v[102:103], v[134:135], off offset:48

.Lrs_a_nl_2_1:
	s_waitcnt vmcnt(0)
	v_pk_fma_f32 v[196:197], v[2:3], v[180:181], v[196:197]
	v_pk_fma_f32 v[198:199], v[4:5], v[182:183], v[198:199]
	v_pk_fma_f32 v[200:201], v[6:7], v[184:185], v[200:201]
	v_pk_fma_f32 v[202:203], v[8:9], v[186:187], v[202:203]
	v_pk_fma_f32 v[204:205], v[10:11], v[188:189], v[204:205]
	v_pk_fma_f32 v[206:207], v[12:13], v[190:191], v[206:207]
	v_pk_fma_f32 v[208:209], v[14:15], v[192:193], v[208:209]
	v_pk_fma_f32 v[210:211], v[16:17], v[194:195], v[210:211]
	global_store_dwordx4 v[100:101], v[196:199], off offset:128
	global_store_dwordx4 v[100:101], v[200:203], off offset:160
	global_store_dwordx4 v[100:101], v[204:207], off offset:192
	global_store_dwordx4 v[100:101], v[208:211], off offset:224
	s_cbranch_vccz .Lrs_a_nx_2_1
	v_pk_fma_f32 v[122:123], v[196:197], v[196:197], v[122:123]
	v_pk_fma_f32 v[122:123], v[198:199], v[198:199], v[122:123]
	v_pk_add_f32 v[138:139], v[138:139], 1.0 op_sel_hi:[1,0]
	v_pk_add_f32 v[140:141], v[140:141], 1.0 op_sel_hi:[1,0]
	v_pk_mul_f32 v[212:213], v[196:197], v[212:213]
	v_pk_mul_f32 v[214:215], v[198:199], v[214:215]
	v_pk_mul_f32 v[212:213], v[212:213], v[138:139]
	v_pk_mul_f32 v[214:215], v[214:215], v[140:141]
	v_cvt_pk_f16_f32 v212, v212, v213
	v_cvt_pk_f16_f32 v213, v214, v215
	v_pk_fma_f32 v[122:123], v[200:201], v[200:201], v[122:123]
	v_pk_fma_f32 v[122:123], v[202:203], v[202:203], v[122:123]
	v_pk_add_f32 v[142:143], v[142:143], 1.0 op_sel_hi:[1,0]
	v_pk_add_f32 v[144:145], v[144:145], 1.0 op_sel_hi:[1,0]
	v_pk_mul_f32 v[216:217], v[200:201], v[216:217]
	v_pk_mul_f32 v[218:219], v[202:203], v[218:219]
	v_pk_mul_f32 v[216:217], v[216:217], v[142:143]
	v_pk_mul_f32 v[218:219], v[218:219], v[144:145]
	v_cvt_pk_f16_f32 v216, v216, v217
	v_cvt_pk_f16_f32 v217, v218, v219
	v_pk_fma_f32 v[122:123], v[204:205], v[204:205], v[122:123]
	v_pk_fma_f32 v[122:123], v[206:207], v[206:207], v[122:123]
	v_pk_add_f32 v[146:147], v[146:147], 1.0 op_sel_hi:[1,0]
	v_pk_add_f32 v[148:149], v[148:149], 1.0 op_sel_hi:[1,0]
	v_pk_mul_f32 v[220:221], v[204:205], v[220:221]
	v_pk_mul_f32 v[222:223], v[206:207], v[222:223]
	v_pk_mul_f32 v[220:221], v[220:221], v[146:147]
	v_pk_mul_f32 v[222:223], v[222:223], v[148:149]
	v_cvt_pk_f16_f32 v220, v220, v221
	v_cvt_pk_f16_f32 v221, v222, v223
	v_pk_fma_f32 v[122:123], v[208:209], v[208:209], v[122:123]
	v_pk_fma_f32 v[122:123], v[210:211], v[210:211], v[122:123]
	v_pk_add_f32 v[118:119], v[118:119], 1.0 op_sel_hi:[1,0]
	v_pk_add_f32 v[120:121], v[120:121], 1.0 op_sel_hi:[1,0]
	v_pk_mul_f32 v[134:135], v[208:209], v[134:135]
	v_pk_mul_f32 v[136:137], v[210:211], v[136:137]
	v_pk_mul_f32 v[134:135], v[134:135], v[118:119]
	v_pk_mul_f32 v[136:137], v[136:137], v[120:121]
	v_cvt_pk_f16_f32 v134, v134, v135
	v_cvt_pk_f16_f32 v135, v136, v137
	s_nop 0
	global_store_dwordx2 v[102:103], v[212:213], off offset:64
	global_store_dwordx2 v[102:103], v[216:217], off offset:80
	global_store_dwordx2 v[102:103], v[220:221], off offset:96
	global_store_dwordx2 v[102:103], v[134:135], off offset:112

.Lrs_a_ns_2:
	s_waitcnt vmcnt(0)
	s_branch .LBB0_37
